# v11_defatom
# baseline (speedup 1.0000x reference)
; __device__ __forceinline__ void gemm_tile(const Params& P, const GArgs& ga, const TileDesc& td, int wid_s) {
;     ...
;       static_for<8>([&](auto ic2) __attribute__((always_inline)) {
;         constexpr int idx = b0 + decltype(ic2)::v; constexpr int ai = idx >> 4, m = (idx >> 2) & 3, j = idx & 3;
;         constexpr int rl = ai * HALF + m * 16 + j; constexpr int q = decltype(ic2)::v;
;         float4 v;
;         v.x = r[q].x + scale * acc[ai][0][m][0][j]; v.y = r[q].y + scale * acc[ai][0][m][1][j];
;         v.z = r[q].z + scale * acc[ai][1][m][0][j]; v.w = r[q].w + scale * acc[ai][1][m][1][j];
;         uint2 o; o.x = pack2(v.x, v.y); o.y = pack2(v.z, v.w);
;         *reinterpret_cast<uint2*>(hb + (size_t)rl * DM) = o;
;         float s = red16(v.x * v.x + v.y * v.y + v.z * v.z + v.w * v.w);
;         if (efr == 0) unsafeAtomicAdd(sso + rl, s);
;       });
.LBB0_603:
	v_lshl_add_u64 v[164:165], v[166:167], 2, s[70:71]
	v_mov_b32_e32 v172, v114
	v_mov_b32_e32 v173, v118
	s_waitcnt vmcnt(7)
	v_pk_fma_f32 v[134:135], s[20:21], v[172:173], v[134:135]
	v_mov_b32_e32 v172, v126
	v_mov_b32_e32 v173, v122
	v_pk_fma_f32 v[136:137], s[20:21], v[172:173], v[136:137]
	v_cvt_pk_bf16_f32 v172, v134, v135
	v_pk_mul_f32 v[134:135], v[134:135], v[134:135]
	v_cvt_pk_bf16_f32 v173, v136, v137
	v_pk_mul_f32 v[136:137], v[136:137], v[136:137]
	v_add_f32_e32 v134, v135, v134
	v_add_f32_e32 v134, v136, v134
	v_add_f32_e32 v134, v137, v134
	v_cmp_eq_u32_e64 s[0:1], 0, v203
	global_store_dwordx2 v[162:163], v[172:173], off nt
	v_add_f32_dpp v134, v134, v134 quad_perm:[1,0,3,2] row_mask:0xf bank_mask:0xf bound_ctrl:1
	s_nop 1
	v_add_f32_dpp v134, v134, v134 quad_perm:[2,3,0,1] row_mask:0xf bank_mask:0xf bound_ctrl:1
	s_nop 1
	v_add_f32_dpp v134, v134, v134 row_ror:4 row_mask:0xf bank_mask:0xf bound_ctrl:1
	s_nop 1
	v_mov_b32_dpp v135, v134 row_ror:8 row_mask:0xf bank_mask:0xf bound_ctrl:1
	s_and_saveexec_b64 s[6:7], s[0:1]
	s_cbranch_execz .LBB0_605
	v_add_f32_e32 v134, v134, v135
	v_mov_b32_e32 v176, v134
.LBB0_605:
	s_or_b64 exec, exec, s[6:7]
	v_mov_b32_e32 v134, v115
	v_mov_b32_e32 v135, v119
	s_waitcnt vmcnt(7)
	v_pk_fma_f32 v[130:131], s[20:21], v[134:135], v[130:131]
	v_mov_b32_e32 v134, v127
	v_mov_b32_e32 v135, v123
	v_pk_fma_f32 v[132:133], s[20:21], v[134:135], v[132:133]
	v_cvt_pk_bf16_f32 v134, v130, v131
	v_pk_mul_f32 v[130:131], v[130:131], v[130:131]
	v_cvt_pk_bf16_f32 v135, v132, v133
	v_pk_mul_f32 v[132:133], v[132:133], v[132:133]
	v_add_f32_e32 v130, v131, v130
	v_add_f32_e32 v130, v132, v130
	v_add_f32_e32 v130, v133, v130
	s_movk_i32 s6, 0x1000
	v_add_co_u32_e32 v136, vcc, s6, v162
	v_add_f32_dpp v130, v130, v130 quad_perm:[1,0,3,2] row_mask:0xf bank_mask:0xf bound_ctrl:1
	s_nop 0
	v_addc_co_u32_e32 v137, vcc, 0, v163, vcc
	v_add_f32_dpp v130, v130, v130 quad_perm:[2,3,0,1] row_mask:0xf bank_mask:0xf bound_ctrl:1
	global_store_dwordx2 v[136:137], v[134:135], off nt
	s_nop 0
	v_add_f32_dpp v130, v130, v130 row_ror:4 row_mask:0xf bank_mask:0xf bound_ctrl:1
	s_nop 1
	v_mov_b32_dpp v131, v130 row_ror:8 row_mask:0xf bank_mask:0xf bound_ctrl:1
	s_and_saveexec_b64 s[6:7], s[0:1]
	s_cbranch_execz .LBB0_607
	v_add_f32_e32 v130, v130, v131
	v_mov_b32_e32 v177, v130
.LBB0_607:
	s_or_b64 exec, exec, s[6:7]
	v_mov_b32_e32 v130, v116
	v_mov_b32_e32 v131, v120
	s_waitcnt vmcnt(7)
	v_pk_fma_f32 v[130:131], s[20:21], v[130:131], v[146:147]
	v_mov_b32_e32 v132, v128
	v_mov_b32_e32 v133, v124
	v_pk_fma_f32 v[132:133], s[20:21], v[132:133], v[148:149]
	v_cvt_pk_bf16_f32 v134, v130, v131
	v_pk_mul_f32 v[130:131], v[130:131], v[130:131]
	v_cvt_pk_bf16_f32 v135, v132, v133
	v_pk_mul_f32 v[132:133], v[132:133], v[132:133]
	v_add_f32_e32 v130, v131, v130
	v_add_f32_e32 v130, v132, v130
	v_add_f32_e32 v130, v133, v130
	v_add_co_u32_e32 v136, vcc, s2, v162
	s_nop 0
	v_add_f32_dpp v130, v130, v130 quad_perm:[1,0,3,2] row_mask:0xf bank_mask:0xf bound_ctrl:1
	v_addc_co_u32_e32 v137, vcc, 0, v163, vcc
	s_nop 0
	v_add_f32_dpp v130, v130, v130 quad_perm:[2,3,0,1] row_mask:0xf bank_mask:0xf bound_ctrl:1
	global_store_dwordx2 v[136:137], v[134:135], off nt
	s_nop 0
	v_add_f32_dpp v130, v130, v130 row_ror:4 row_mask:0xf bank_mask:0xf bound_ctrl:1
	s_nop 1
	v_mov_b32_dpp v131, v130 row_ror:8 row_mask:0xf bank_mask:0xf bound_ctrl:1
	s_and_saveexec_b64 s[6:7], s[0:1]
	s_cbranch_execz .LBB0_609
	v_add_f32_e32 v130, v130, v131
	v_mov_b32_e32 v178, v130
.LBB0_609:
	s_or_b64 exec, exec, s[6:7]
	v_mov_b32_e32 v130, v117
	v_mov_b32_e32 v131, v121
	s_waitcnt vmcnt(7)
	v_pk_fma_f32 v[130:131], s[20:21], v[130:131], v[138:139]
	v_mov_b32_e32 v132, v129
	v_mov_b32_e32 v133, v125
	v_pk_fma_f32 v[132:133], s[20:21], v[132:133], v[140:141]
	v_cvt_pk_bf16_f32 v134, v130, v131
	v_pk_mul_f32 v[130:131], v[130:131], v[130:131]
	v_cvt_pk_bf16_f32 v135, v132, v133
	v_pk_mul_f32 v[132:133], v[132:133], v[132:133]
	v_add_f32_e32 v130, v131, v130
	v_add_f32_e32 v130, v132, v130
	v_add_f32_e32 v130, v133, v130
	v_add_co_u32_e32 v136, vcc, s55, v162
	s_nop 0
	v_add_f32_dpp v130, v130, v130 quad_perm:[1,0,3,2] row_mask:0xf bank_mask:0xf bound_ctrl:1
	v_addc_co_u32_e32 v137, vcc, 0, v163, vcc
	s_nop 0
	v_add_f32_dpp v130, v130, v130 quad_perm:[2,3,0,1] row_mask:0xf bank_mask:0xf bound_ctrl:1
	global_store_dwordx2 v[136:137], v[134:135], off nt
	s_nop 0
	v_add_f32_dpp v130, v130, v130 row_ror:4 row_mask:0xf bank_mask:0xf bound_ctrl:1
	s_nop 1
	v_mov_b32_dpp v131, v130 row_ror:8 row_mask:0xf bank_mask:0xf bound_ctrl:1
	s_and_saveexec_b64 s[6:7], s[0:1]
	s_cbranch_execz .LBB0_611
	v_add_f32_e32 v130, v130, v131
	v_mov_b32_e32 v179, v130
; __device__ __forceinline__ void gemm_tile(const Params& P, const GArgs& ga, const TileDesc& td, int wid_s) {
;     ...
;       static_for<8>([&](auto ic2) __attribute__((always_inline)) {
;         constexpr int idx = b0 + decltype(ic2)::v; constexpr int ai = idx >> 4, m = (idx >> 2) & 3, j = idx & 3;
;         constexpr int rl = ai * HALF + m * 16 + j; constexpr int q = decltype(ic2)::v;
;         float4 v;
;         v.x = r[q].x + scale * acc[ai][0][m][0][j]; v.y = r[q].y + scale * acc[ai][0][m][1][j];
;         v.z = r[q].z + scale * acc[ai][1][m][0][j]; v.w = r[q].w + scale * acc[ai][1][m][1][j];
;         uint2 o; o.x = pack2(v.x, v.y); o.y = pack2(v.z, v.w);
;         *reinterpret_cast<uint2*>(hb + (size_t)rl * DM) = o;
;         float s = red16(v.x * v.x + v.y * v.y + v.z * v.z + v.w * v.w);
;         if (efr == 0) unsafeAtomicAdd(sso + rl, s);
;       });
.LBB0_611:
	s_or_b64 exec, exec, s[6:7]
	v_mov_b32_e32 v130, v98
	v_mov_b32_e32 v131, v102
	s_waitcnt vmcnt(7)
	v_pk_fma_f32 v[130:131], s[20:21], v[130:131], v[154:155]
	v_mov_b32_e32 v132, v110
	v_mov_b32_e32 v133, v106
	v_pk_fma_f32 v[132:133], s[20:21], v[132:133], v[156:157]
	v_cvt_pk_bf16_f32 v134, v130, v131
	v_pk_mul_f32 v[130:131], v[130:131], v[130:131]
	v_cvt_pk_bf16_f32 v135, v132, v133
	v_pk_mul_f32 v[132:133], v[132:133], v[132:133]
	v_add_f32_e32 v130, v131, v130
	v_add_f32_e32 v130, v132, v130
	v_add_f32_e32 v130, v133, v130
	s_mov_b32 s6, 0x10000
	v_add_co_u32_e32 v136, vcc, s6, v162
	v_add_f32_dpp v130, v130, v130 quad_perm:[1,0,3,2] row_mask:0xf bank_mask:0xf bound_ctrl:1
	s_nop 0
	v_addc_co_u32_e32 v137, vcc, 0, v163, vcc
	v_add_f32_dpp v130, v130, v130 quad_perm:[2,3,0,1] row_mask:0xf bank_mask:0xf bound_ctrl:1
	global_store_dwordx2 v[136:137], v[134:135], off nt
	s_nop 0
	v_add_f32_dpp v130, v130, v130 row_ror:4 row_mask:0xf bank_mask:0xf bound_ctrl:1
	s_nop 1
	v_mov_b32_dpp v131, v130 row_ror:8 row_mask:0xf bank_mask:0xf bound_ctrl:1
	s_and_saveexec_b64 s[6:7], s[0:1]
	s_cbranch_execz .LBB0_613
	v_add_f32_e32 v130, v130, v131
	v_mov_b32_e32 v180, v130
.LBB0_613:
	s_or_b64 exec, exec, s[6:7]
	v_mov_b32_e32 v130, v99
	v_mov_b32_e32 v131, v103
	s_waitcnt vmcnt(7)
	v_pk_fma_f32 v[130:131], s[20:21], v[130:131], v[142:143]
	v_mov_b32_e32 v132, v111
	v_mov_b32_e32 v133, v107
	v_pk_fma_f32 v[132:133], s[20:21], v[132:133], v[144:145]
	v_cvt_pk_bf16_f32 v134, v130, v131
	v_pk_mul_f32 v[130:131], v[130:131], v[130:131]
	v_cvt_pk_bf16_f32 v135, v132, v133
	v_pk_mul_f32 v[132:133], v[132:133], v[132:133]
	v_add_f32_e32 v130, v131, v130
	v_add_f32_e32 v130, v132, v130
	v_add_f32_e32 v130, v133, v130
	v_add_co_u32_e32 v136, vcc, s13, v162
	s_nop 0
	v_add_f32_dpp v130, v130, v130 quad_perm:[1,0,3,2] row_mask:0xf bank_mask:0xf bound_ctrl:1
	v_addc_co_u32_e32 v137, vcc, 0, v163, vcc
	s_nop 0
	v_add_f32_dpp v130, v130, v130 quad_perm:[2,3,0,1] row_mask:0xf bank_mask:0xf bound_ctrl:1
	global_store_dwordx2 v[136:137], v[134:135], off nt
	s_nop 0
	v_add_f32_dpp v130, v130, v130 row_ror:4 row_mask:0xf bank_mask:0xf bound_ctrl:1
	s_nop 1
	v_mov_b32_dpp v131, v130 row_ror:8 row_mask:0xf bank_mask:0xf bound_ctrl:1
	s_and_saveexec_b64 s[6:7], s[0:1]
	s_cbranch_execz .LBB0_615
	v_add_f32_e32 v130, v130, v131
	v_mov_b32_e32 v181, v130
.LBB0_615:
	s_or_b64 exec, exec, s[6:7]
	v_mov_b32_e32 v130, v100
	v_mov_b32_e32 v131, v104
	s_waitcnt vmcnt(7)
	v_pk_fma_f32 v[130:131], s[20:21], v[130:131], v[150:151]
	v_mov_b32_e32 v132, v112
	v_mov_b32_e32 v133, v108
	v_pk_fma_f32 v[132:133], s[20:21], v[132:133], v[152:153]
	v_cvt_pk_bf16_f32 v134, v130, v131
	v_pk_mul_f32 v[130:131], v[130:131], v[130:131]
	v_cvt_pk_bf16_f32 v135, v132, v133
	v_pk_mul_f32 v[132:133], v[132:133], v[132:133]
	v_add_f32_e32 v130, v131, v130
	v_add_f32_e32 v130, v132, v130
	v_add_f32_e32 v130, v133, v130
	v_add_co_u32_e32 v136, vcc, s67, v162
	s_nop 0
	v_add_f32_dpp v130, v130, v130 quad_perm:[1,0,3,2] row_mask:0xf bank_mask:0xf bound_ctrl:1
	v_addc_co_u32_e32 v137, vcc, 0, v163, vcc
	s_nop 0
	v_add_f32_dpp v130, v130, v130 quad_perm:[2,3,0,1] row_mask:0xf bank_mask:0xf bound_ctrl:1
	global_store_dwordx2 v[136:137], v[134:135], off nt
	s_nop 0
	v_add_f32_dpp v130, v130, v130 row_ror:4 row_mask:0xf bank_mask:0xf bound_ctrl:1
	s_nop 1
	v_mov_b32_dpp v131, v130 row_ror:8 row_mask:0xf bank_mask:0xf bound_ctrl:1
	s_and_saveexec_b64 s[6:7], s[0:1]
	s_cbranch_execz .LBB0_617
	v_add_f32_e32 v130, v130, v131
	v_mov_b32_e32 v182, v130
.LBB0_617:
	s_or_b64 exec, exec, s[6:7]
	v_mov_b32_e32 v130, v101
	v_mov_b32_e32 v131, v105
	s_waitcnt vmcnt(7)
	v_pk_fma_f32 v[130:131], s[20:21], v[130:131], v[158:159]
	v_mov_b32_e32 v132, v113
	v_mov_b32_e32 v133, v109
	v_pk_fma_f32 v[132:133], s[20:21], v[132:133], v[160:161]
	v_cvt_pk_bf16_f32 v134, v130, v131
	v_pk_mul_f32 v[130:131], v[130:131], v[130:131]
	v_cvt_pk_bf16_f32 v135, v132, v133
	v_pk_mul_f32 v[132:133], v[132:133], v[132:133]
	v_add_f32_e32 v130, v131, v130
	v_add_f32_e32 v130, v132, v130
	v_add_f32_e32 v130, v133, v130
	v_add_co_u32_e32 v136, vcc, s14, v162
	s_nop 0
	v_add_f32_dpp v130, v130, v130 quad_perm:[1,0,3,2] row_mask:0xf bank_mask:0xf bound_ctrl:1
	v_addc_co_u32_e32 v137, vcc, 0, v163, vcc
	s_nop 0
	v_add_f32_dpp v130, v130, v130 quad_perm:[2,3,0,1] row_mask:0xf bank_mask:0xf bound_ctrl:1
	global_store_dwordx2 v[136:137], v[134:135], off nt
	s_nop 0
	v_add_f32_dpp v130, v130, v130 row_ror:4 row_mask:0xf bank_mask:0xf bound_ctrl:1
	s_nop 1
	v_mov_b32_dpp v131, v130 row_ror:8 row_mask:0xf bank_mask:0xf bound_ctrl:1
	s_and_saveexec_b64 s[6:7], s[0:1]
	s_cbranch_execz .LBB0_619
	v_add_f32_e32 v130, v130, v131
	v_mov_b32_e32 v183, v130

; __device__ __forceinline__ void gemm_tile(const Params& P, const GArgs& ga, const TileDesc& td, int wid_s) {
;     ...
;       static_for<8>([&](auto ic2) __attribute__((always_inline)) {
;         constexpr int idx = b0 + decltype(ic2)::v; constexpr int ai = idx >> 4, m = (idx >> 2) & 3, j = idx & 3;
;         constexpr int rl = ai * HALF + m * 16 + j; constexpr int q = decltype(ic2)::v;
;         float4 v;
;         v.x = r[q].x + scale * acc[ai][0][m][0][j]; v.y = r[q].y + scale * acc[ai][0][m][1][j];
;         v.z = r[q].z + scale * acc[ai][1][m][0][j]; v.w = r[q].w + scale * acc[ai][1][m][1][j];
;         uint2 o; o.x = pack2(v.x, v.y); o.y = pack2(v.z, v.w);
;         *reinterpret_cast<uint2*>(hb + (size_t)rl * DM) = o;
;         float s = red16(v.x * v.x + v.y * v.y + v.z * v.z + v.w * v.w);
;         if (efr == 0) unsafeAtomicAdd(sso + rl, s);
;       });
.LBB0_623:
	v_mov_b32_e32 v172, v82
	v_mov_b32_e32 v173, v86
	s_waitcnt vmcnt(7)
	v_pk_fma_f32 v[158:159], s[20:21], v[172:173], v[158:159]
	v_mov_b32_e32 v172, v94
	v_mov_b32_e32 v173, v90
	v_pk_fma_f32 v[160:161], s[20:21], v[172:173], v[160:161]
	v_cvt_pk_bf16_f32 v172, v158, v159
	v_pk_mul_f32 v[158:159], v[158:159], v[158:159]
	v_cvt_pk_bf16_f32 v173, v160, v161
	v_pk_mul_f32 v[160:161], v[160:161], v[160:161]
	v_add_f32_e32 v158, v159, v158
	v_add_f32_e32 v158, v160, v158
	v_add_f32_e32 v158, v161, v158
	v_add_co_u32_e32 v174, vcc, s11, v162
	s_nop 0
	v_add_f32_dpp v158, v158, v158 quad_perm:[1,0,3,2] row_mask:0xf bank_mask:0xf bound_ctrl:1
	v_addc_co_u32_e32 v175, vcc, 0, v163, vcc
	s_nop 0
	v_add_f32_dpp v158, v158, v158 quad_perm:[2,3,0,1] row_mask:0xf bank_mask:0xf bound_ctrl:1
	global_store_dwordx2 v[174:175], v[172:173], off nt
	s_nop 0
	v_add_f32_dpp v158, v158, v158 row_ror:4 row_mask:0xf bank_mask:0xf bound_ctrl:1
	s_nop 1
	v_mov_b32_dpp v159, v158 row_ror:8 row_mask:0xf bank_mask:0xf bound_ctrl:1
	s_and_saveexec_b64 s[6:7], s[0:1]
	s_cbranch_execz .LBB0_625
	v_add_f32_e32 v158, v158, v159
	v_mov_b32_e32 v184, v158
.LBB0_625:
	s_or_b64 exec, exec, s[6:7]
	v_mov_b32_e32 v158, v83
	v_mov_b32_e32 v159, v87
	s_waitcnt vmcnt(7)
	v_pk_fma_f32 v[154:155], s[20:21], v[158:159], v[154:155]
	v_mov_b32_e32 v158, v95
	v_mov_b32_e32 v159, v91
	v_pk_fma_f32 v[156:157], s[20:21], v[158:159], v[156:157]
	v_cvt_pk_bf16_f32 v158, v154, v155
	v_pk_mul_f32 v[154:155], v[154:155], v[154:155]
	v_cvt_pk_bf16_f32 v159, v156, v157
	v_pk_mul_f32 v[156:157], v[156:157], v[156:157]
	v_add_f32_e32 v154, v155, v154
	v_add_f32_e32 v154, v156, v154
	v_add_f32_e32 v154, v157, v154
	s_mov_b32 s6, 0x21000
	v_add_co_u32_e32 v160, vcc, s6, v162
	v_add_f32_dpp v154, v154, v154 quad_perm:[1,0,3,2] row_mask:0xf bank_mask:0xf bound_ctrl:1
	s_nop 0
	v_addc_co_u32_e32 v161, vcc, 0, v163, vcc
	v_add_f32_dpp v154, v154, v154 quad_perm:[2,3,0,1] row_mask:0xf bank_mask:0xf bound_ctrl:1
	global_store_dwordx2 v[160:161], v[158:159], off nt
	s_nop 0
	v_add_f32_dpp v154, v154, v154 row_ror:4 row_mask:0xf bank_mask:0xf bound_ctrl:1
	s_nop 1
	v_mov_b32_dpp v155, v154 row_ror:8 row_mask:0xf bank_mask:0xf bound_ctrl:1
	s_and_saveexec_b64 s[6:7], s[0:1]
	s_cbranch_execz .LBB0_627
	v_add_f32_e32 v154, v154, v155
	v_mov_b32_e32 v185, v154
.LBB0_627:
	s_or_b64 exec, exec, s[6:7]
	v_mov_b32_e32 v154, v84
	v_mov_b32_e32 v155, v88
	s_waitcnt vmcnt(7)
	v_pk_fma_f32 v[150:151], s[20:21], v[154:155], v[150:151]
	v_mov_b32_e32 v154, v96
	v_mov_b32_e32 v155, v92
	v_pk_fma_f32 v[152:153], s[20:21], v[154:155], v[152:153]
	v_cvt_pk_bf16_f32 v154, v150, v151
	v_pk_mul_f32 v[150:151], v[150:151], v[150:151]
	v_cvt_pk_bf16_f32 v155, v152, v153
	v_pk_mul_f32 v[152:153], v[152:153], v[152:153]
	v_add_f32_e32 v150, v151, v150
	v_add_f32_e32 v150, v152, v150
	v_add_f32_e32 v150, v153, v150
	s_mov_b32 s6, 0x22000
	v_add_co_u32_e32 v156, vcc, s6, v162
	v_add_f32_dpp v150, v150, v150 quad_perm:[1,0,3,2] row_mask:0xf bank_mask:0xf bound_ctrl:1
	s_nop 0
	v_addc_co_u32_e32 v157, vcc, 0, v163, vcc
	v_add_f32_dpp v150, v150, v150 quad_perm:[2,3,0,1] row_mask:0xf bank_mask:0xf bound_ctrl:1
	global_store_dwordx2 v[156:157], v[154:155], off nt
	s_nop 0
	v_add_f32_dpp v150, v150, v150 row_ror:4 row_mask:0xf bank_mask:0xf bound_ctrl:1
	s_nop 1
	v_mov_b32_dpp v151, v150 row_ror:8 row_mask:0xf bank_mask:0xf bound_ctrl:1
	s_and_saveexec_b64 s[6:7], s[0:1]
	s_cbranch_execz .LBB0_629
	v_add_f32_e32 v150, v150, v151
	v_mov_b32_e32 v186, v150
.LBB0_629:
	s_or_b64 exec, exec, s[6:7]
	v_mov_b32_e32 v150, v85
	v_mov_b32_e32 v151, v89
	s_waitcnt vmcnt(7)
	v_pk_fma_f32 v[146:147], s[20:21], v[150:151], v[146:147]
	v_mov_b32_e32 v150, v97
	v_mov_b32_e32 v151, v93
	v_pk_fma_f32 v[148:149], s[20:21], v[150:151], v[148:149]
	v_cvt_pk_bf16_f32 v150, v146, v147
	v_pk_mul_f32 v[146:147], v[146:147], v[146:147]
	v_cvt_pk_bf16_f32 v151, v148, v149
	v_pk_mul_f32 v[148:149], v[148:149], v[148:149]
	v_add_f32_e32 v146, v147, v146
	v_add_f32_e32 v146, v148, v146
	v_add_f32_e32 v146, v149, v146
	s_mov_b32 s6, 0x23000
	v_add_co_u32_e32 v152, vcc, s6, v162
	v_add_f32_dpp v146, v146, v146 quad_perm:[1,0,3,2] row_mask:0xf bank_mask:0xf bound_ctrl:1
	s_nop 0
	v_addc_co_u32_e32 v153, vcc, 0, v163, vcc
	v_add_f32_dpp v146, v146, v146 quad_perm:[2,3,0,1] row_mask:0xf bank_mask:0xf bound_ctrl:1
	global_store_dwordx2 v[152:153], v[150:151], off nt
	s_nop 0
	v_add_f32_dpp v146, v146, v146 row_ror:4 row_mask:0xf bank_mask:0xf bound_ctrl:1
	s_nop 1
	v_mov_b32_dpp v147, v146 row_ror:8 row_mask:0xf bank_mask:0xf bound_ctrl:1
	s_and_saveexec_b64 s[6:7], s[0:1]
	s_cbranch_execz .LBB0_631
	v_add_f32_e32 v146, v146, v147
	v_mov_b32_e32 v187, v146
; __device__ __forceinline__ void gemm_tile(const Params& P, const GArgs& ga, const TileDesc& td, int wid_s) {
;     ...
;       static_for<8>([&](auto ic2) __attribute__((always_inline)) {
;         constexpr int idx = b0 + decltype(ic2)::v; constexpr int ai = idx >> 4, m = (idx >> 2) & 3, j = idx & 3;
;         constexpr int rl = ai * HALF + m * 16 + j; constexpr int q = decltype(ic2)::v;
;         float4 v;
;         v.x = r[q].x + scale * acc[ai][0][m][0][j]; v.y = r[q].y + scale * acc[ai][0][m][1][j];
;         v.z = r[q].z + scale * acc[ai][1][m][0][j]; v.w = r[q].w + scale * acc[ai][1][m][1][j];
;         uint2 o; o.x = pack2(v.x, v.y); o.y = pack2(v.z, v.w);
;         *reinterpret_cast<uint2*>(hb + (size_t)rl * DM) = o;
;         float s = red16(v.x * v.x + v.y * v.y + v.z * v.z + v.w * v.w);
;         if (efr == 0) unsafeAtomicAdd(sso + rl, s);
;       });
.LBB0_631:
	s_or_b64 exec, exec, s[6:7]
	v_mov_b32_e32 v146, v66
	v_mov_b32_e32 v147, v70
	s_waitcnt vmcnt(7)
	v_pk_fma_f32 v[142:143], s[20:21], v[146:147], v[142:143]
	v_mov_b32_e32 v146, v78
	v_mov_b32_e32 v147, v74
	v_pk_fma_f32 v[144:145], s[20:21], v[146:147], v[144:145]
	v_cvt_pk_bf16_f32 v146, v142, v143
	v_pk_mul_f32 v[142:143], v[142:143], v[142:143]
	v_cvt_pk_bf16_f32 v147, v144, v145
	v_pk_mul_f32 v[144:145], v[144:145], v[144:145]
	v_add_f32_e32 v142, v143, v142
	v_add_f32_e32 v142, v144, v142
	v_add_f32_e32 v142, v145, v142
	s_mov_b32 s6, 0x30000
	v_add_co_u32_e32 v148, vcc, s6, v162
	v_add_f32_dpp v142, v142, v142 quad_perm:[1,0,3,2] row_mask:0xf bank_mask:0xf bound_ctrl:1
	s_nop 0
	v_addc_co_u32_e32 v149, vcc, 0, v163, vcc
	v_add_f32_dpp v142, v142, v142 quad_perm:[2,3,0,1] row_mask:0xf bank_mask:0xf bound_ctrl:1
	global_store_dwordx2 v[148:149], v[146:147], off nt
	s_nop 0
	v_add_f32_dpp v142, v142, v142 row_ror:4 row_mask:0xf bank_mask:0xf bound_ctrl:1
	s_nop 1
	v_mov_b32_dpp v143, v142 row_ror:8 row_mask:0xf bank_mask:0xf bound_ctrl:1
	s_and_saveexec_b64 s[6:7], s[0:1]
	s_cbranch_execz .LBB0_633
	v_add_f32_e32 v142, v142, v143
	v_mov_b32_e32 v188, v142
.LBB0_633:
	s_or_b64 exec, exec, s[6:7]
	v_mov_b32_e32 v142, v67
	v_mov_b32_e32 v143, v71
	s_waitcnt vmcnt(7)
	v_pk_fma_f32 v[138:139], s[20:21], v[142:143], v[138:139]
	v_mov_b32_e32 v142, v79
	v_mov_b32_e32 v143, v75
	v_pk_fma_f32 v[140:141], s[20:21], v[142:143], v[140:141]
	v_cvt_pk_bf16_f32 v142, v138, v139
	v_pk_mul_f32 v[138:139], v[138:139], v[138:139]
	v_cvt_pk_bf16_f32 v143, v140, v141
	v_pk_mul_f32 v[140:141], v[140:141], v[140:141]
	v_add_f32_e32 v138, v139, v138
	v_add_f32_e32 v138, v140, v138
	v_add_f32_e32 v138, v141, v138
	v_add_co_u32_e32 v144, vcc, s19, v162
	s_nop 0
	v_add_f32_dpp v138, v138, v138 quad_perm:[1,0,3,2] row_mask:0xf bank_mask:0xf bound_ctrl:1
	v_addc_co_u32_e32 v145, vcc, 0, v163, vcc
	s_nop 0
	v_add_f32_dpp v138, v138, v138 quad_perm:[2,3,0,1] row_mask:0xf bank_mask:0xf bound_ctrl:1
	global_store_dwordx2 v[144:145], v[142:143], off nt
	s_nop 0
	v_add_f32_dpp v138, v138, v138 row_ror:4 row_mask:0xf bank_mask:0xf bound_ctrl:1
	s_nop 1
	v_mov_b32_dpp v139, v138 row_ror:8 row_mask:0xf bank_mask:0xf bound_ctrl:1
	s_and_saveexec_b64 s[6:7], s[0:1]
	s_cbranch_execz .LBB0_635
	v_add_f32_e32 v138, v138, v139
	v_mov_b32_e32 v189, v138
.LBB0_635:
	s_or_b64 exec, exec, s[6:7]
	v_mov_b32_e32 v138, v68
	v_mov_b32_e32 v139, v72
	s_waitcnt vmcnt(7)
	v_pk_fma_f32 v[134:135], s[20:21], v[138:139], v[134:135]
	v_mov_b32_e32 v138, v80
	v_mov_b32_e32 v139, v76
	v_pk_fma_f32 v[136:137], s[20:21], v[138:139], v[136:137]
	v_cvt_pk_bf16_f32 v138, v134, v135
	v_pk_mul_f32 v[134:135], v[134:135], v[134:135]
	v_cvt_pk_bf16_f32 v139, v136, v137
	v_pk_mul_f32 v[136:137], v[136:137], v[136:137]
	v_add_f32_e32 v134, v135, v134
	v_add_f32_e32 v134, v136, v134
	v_add_f32_e32 v134, v137, v134
	s_mov_b32 s6, 0x32000
	v_add_co_u32_e32 v140, vcc, s6, v162
	v_add_f32_dpp v134, v134, v134 quad_perm:[1,0,3,2] row_mask:0xf bank_mask:0xf bound_ctrl:1
	s_nop 0
	v_addc_co_u32_e32 v141, vcc, 0, v163, vcc
	v_add_f32_dpp v134, v134, v134 quad_perm:[2,3,0,1] row_mask:0xf bank_mask:0xf bound_ctrl:1
	global_store_dwordx2 v[140:141], v[138:139], off nt
	s_nop 0
	v_add_f32_dpp v134, v134, v134 row_ror:4 row_mask:0xf bank_mask:0xf bound_ctrl:1
	s_nop 1
	v_mov_b32_dpp v135, v134 row_ror:8 row_mask:0xf bank_mask:0xf bound_ctrl:1
	s_and_saveexec_b64 s[6:7], s[0:1]
	s_cbranch_execz .LBB0_637
	v_add_f32_e32 v134, v134, v135
	v_mov_b32_e32 v190, v134
.LBB0_637:
	s_or_b64 exec, exec, s[6:7]
	v_mov_b32_e32 v134, v69
	v_mov_b32_e32 v135, v73
	s_waitcnt vmcnt(7)
	v_pk_fma_f32 v[130:131], s[20:21], v[134:135], v[130:131]
	v_mov_b32_e32 v134, v81
	v_mov_b32_e32 v135, v77
	v_pk_fma_f32 v[132:133], s[20:21], v[134:135], v[132:133]
	v_cvt_pk_bf16_f32 v134, v130, v131
	v_pk_mul_f32 v[130:131], v[130:131], v[130:131]
	v_cvt_pk_bf16_f32 v135, v132, v133
	v_pk_mul_f32 v[132:133], v[132:133], v[132:133]
	v_add_f32_e32 v130, v131, v130
	v_add_f32_e32 v130, v132, v130
	v_add_f32_e32 v130, v133, v130
	s_mov_b32 s6, 0x33000
	v_add_co_u32_e32 v136, vcc, s6, v162
	v_add_f32_dpp v130, v130, v130 quad_perm:[1,0,3,2] row_mask:0xf bank_mask:0xf bound_ctrl:1
	s_nop 0
	v_addc_co_u32_e32 v137, vcc, 0, v163, vcc
	v_add_f32_dpp v130, v130, v130 quad_perm:[2,3,0,1] row_mask:0xf bank_mask:0xf bound_ctrl:1
	global_store_dwordx2 v[136:137], v[134:135], off nt
	s_nop 0
	v_add_f32_dpp v130, v130, v130 row_ror:4 row_mask:0xf bank_mask:0xf bound_ctrl:1
	s_nop 1
	v_mov_b32_dpp v131, v130 row_ror:8 row_mask:0xf bank_mask:0xf bound_ctrl:1
	s_and_saveexec_b64 s[6:7], s[0:1]
	s_cbranch_execz .LBB0_639
	v_add_f32_e32 v130, v130, v131
	v_mov_b32_e32 v191, v130

; __device__ __forceinline__ void gemm_tile(const Params& P, const GArgs& ga, const TileDesc& td, int wid_s) {
;     ...
;       static_for<8>([&](auto ic2) __attribute__((always_inline)) {
;         constexpr int idx = b0 + decltype(ic2)::v; constexpr int ai = idx >> 4, m = (idx >> 2) & 3, j = idx & 3;
;         constexpr int rl = ai * HALF + m * 16 + j; constexpr int q = decltype(ic2)::v;
;         float4 v;
;         v.x = r[q].x + scale * acc[ai][0][m][0][j]; v.y = r[q].y + scale * acc[ai][0][m][1][j];
;         v.z = r[q].z + scale * acc[ai][1][m][0][j]; v.w = r[q].w + scale * acc[ai][1][m][1][j];
;         uint2 o; o.x = pack2(v.x, v.y); o.y = pack2(v.z, v.w);
;         *reinterpret_cast<uint2*>(hb + (size_t)rl * DM) = o;
;         float s = red16(v.x * v.x + v.y * v.y + v.z * v.z + v.w * v.w);
;         if (efr == 0) unsafeAtomicAdd(sso + rl, s);
;       });
.LBB0_643:
	v_mov_b32_e32 v172, v50
	v_mov_b32_e32 v173, v54
	s_waitcnt vmcnt(7)
	v_pk_fma_f32 v[158:159], s[20:21], v[172:173], v[158:159]
	v_mov_b32_e32 v172, v62
	v_mov_b32_e32 v173, v58
	v_pk_fma_f32 v[160:161], s[20:21], v[172:173], v[160:161]
	v_cvt_pk_bf16_f32 v172, v158, v159
	v_pk_mul_f32 v[158:159], v[158:159], v[158:159]
	v_cvt_pk_bf16_f32 v173, v160, v161
	v_pk_mul_f32 v[160:161], v[160:161], v[160:161]
	v_add_f32_e32 v158, v159, v158
	v_add_f32_e32 v158, v160, v158
	v_add_f32_e32 v158, v161, v158
	s_mov_b32 s6, 0x80000
	v_add_co_u32_e32 v174, vcc, s6, v162
	v_add_f32_dpp v158, v158, v158 quad_perm:[1,0,3,2] row_mask:0xf bank_mask:0xf bound_ctrl:1
	s_nop 0
	v_addc_co_u32_e32 v175, vcc, 0, v163, vcc
	v_add_f32_dpp v158, v158, v158 quad_perm:[2,3,0,1] row_mask:0xf bank_mask:0xf bound_ctrl:1
	global_store_dwordx2 v[174:175], v[172:173], off nt
	s_nop 0
	v_add_f32_dpp v158, v158, v158 row_ror:4 row_mask:0xf bank_mask:0xf bound_ctrl:1
	s_nop 1
	v_mov_b32_dpp v159, v158 row_ror:8 row_mask:0xf bank_mask:0xf bound_ctrl:1
	s_and_saveexec_b64 s[6:7], s[0:1]
	s_cbranch_execz .LBB0_645
	v_add_f32_e32 v158, v158, v159
	v_mov_b32_e32 v192, v158
.LBB0_645:
	s_or_b64 exec, exec, s[6:7]
	v_mov_b32_e32 v158, v51
	v_mov_b32_e32 v159, v55
	s_waitcnt vmcnt(7)
	v_pk_fma_f32 v[154:155], s[20:21], v[158:159], v[154:155]
	v_mov_b32_e32 v158, v63
	v_mov_b32_e32 v159, v59
	v_pk_fma_f32 v[156:157], s[20:21], v[158:159], v[156:157]
	v_cvt_pk_bf16_f32 v158, v154, v155
	v_pk_mul_f32 v[154:155], v[154:155], v[154:155]
	v_cvt_pk_bf16_f32 v159, v156, v157
	v_pk_mul_f32 v[156:157], v[156:157], v[156:157]
	v_add_f32_e32 v154, v155, v154
	v_add_f32_e32 v154, v156, v154
	v_add_f32_e32 v154, v157, v154
	s_mov_b32 s6, 0x81000
	v_add_co_u32_e32 v160, vcc, s6, v162
	v_add_f32_dpp v154, v154, v154 quad_perm:[1,0,3,2] row_mask:0xf bank_mask:0xf bound_ctrl:1
	s_nop 0
	v_addc_co_u32_e32 v161, vcc, 0, v163, vcc
	v_add_f32_dpp v154, v154, v154 quad_perm:[2,3,0,1] row_mask:0xf bank_mask:0xf bound_ctrl:1
	global_store_dwordx2 v[160:161], v[158:159], off nt
	s_nop 0
	v_add_f32_dpp v154, v154, v154 row_ror:4 row_mask:0xf bank_mask:0xf bound_ctrl:1
	s_nop 1
	v_mov_b32_dpp v155, v154 row_ror:8 row_mask:0xf bank_mask:0xf bound_ctrl:1
	s_and_saveexec_b64 s[6:7], s[0:1]
	s_cbranch_execz .LBB0_647
	v_add_f32_e32 v154, v154, v155
	v_mov_b32_e32 v193, v154
.LBB0_647:
	s_or_b64 exec, exec, s[6:7]
	v_mov_b32_e32 v154, v52
	v_mov_b32_e32 v155, v56
	s_waitcnt vmcnt(7)
	v_pk_fma_f32 v[150:151], s[20:21], v[154:155], v[150:151]
	v_mov_b32_e32 v154, v64
	v_mov_b32_e32 v155, v60
	v_pk_fma_f32 v[152:153], s[20:21], v[154:155], v[152:153]
	v_cvt_pk_bf16_f32 v154, v150, v151
	v_pk_mul_f32 v[150:151], v[150:151], v[150:151]
	v_cvt_pk_bf16_f32 v155, v152, v153
	v_pk_mul_f32 v[152:153], v[152:153], v[152:153]
	v_add_f32_e32 v150, v151, v150
	v_add_f32_e32 v150, v152, v150
	v_add_f32_e32 v150, v153, v150
	s_mov_b32 s6, 0x82000
	v_add_co_u32_e32 v156, vcc, s6, v162
	v_add_f32_dpp v150, v150, v150 quad_perm:[1,0,3,2] row_mask:0xf bank_mask:0xf bound_ctrl:1
	s_nop 0
	v_addc_co_u32_e32 v157, vcc, 0, v163, vcc
	v_add_f32_dpp v150, v150, v150 quad_perm:[2,3,0,1] row_mask:0xf bank_mask:0xf bound_ctrl:1
	global_store_dwordx2 v[156:157], v[154:155], off nt
	s_nop 0
	v_add_f32_dpp v150, v150, v150 row_ror:4 row_mask:0xf bank_mask:0xf bound_ctrl:1
	s_nop 1
	v_mov_b32_dpp v151, v150 row_ror:8 row_mask:0xf bank_mask:0xf bound_ctrl:1
	s_and_saveexec_b64 s[6:7], s[0:1]
	s_cbranch_execz .LBB0_649
	v_add_f32_e32 v150, v150, v151
	v_mov_b32_e32 v194, v150
.LBB0_649:
	s_or_b64 exec, exec, s[6:7]
	v_mov_b32_e32 v150, v53
	v_mov_b32_e32 v151, v57
	s_waitcnt vmcnt(7)
	v_pk_fma_f32 v[146:147], s[20:21], v[150:151], v[146:147]
	v_mov_b32_e32 v150, v65
	v_mov_b32_e32 v151, v61
	v_pk_fma_f32 v[148:149], s[20:21], v[150:151], v[148:149]
	v_cvt_pk_bf16_f32 v150, v146, v147
	v_pk_mul_f32 v[146:147], v[146:147], v[146:147]
	v_cvt_pk_bf16_f32 v151, v148, v149
	v_pk_mul_f32 v[148:149], v[148:149], v[148:149]
	v_add_f32_e32 v146, v147, v146
	v_add_f32_e32 v146, v148, v146
	v_add_f32_e32 v146, v149, v146
	s_mov_b32 s6, 0x83000
	v_add_co_u32_e32 v152, vcc, s6, v162
	v_add_f32_dpp v146, v146, v146 quad_perm:[1,0,3,2] row_mask:0xf bank_mask:0xf bound_ctrl:1
	s_nop 0
	v_addc_co_u32_e32 v153, vcc, 0, v163, vcc
	v_add_f32_dpp v146, v146, v146 quad_perm:[2,3,0,1] row_mask:0xf bank_mask:0xf bound_ctrl:1
	global_store_dwordx2 v[152:153], v[150:151], off nt
	s_nop 0
	v_add_f32_dpp v146, v146, v146 row_ror:4 row_mask:0xf bank_mask:0xf bound_ctrl:1
	s_nop 1
	v_mov_b32_dpp v147, v146 row_ror:8 row_mask:0xf bank_mask:0xf bound_ctrl:1
	s_and_saveexec_b64 s[6:7], s[0:1]
	s_cbranch_execz .LBB0_651
	v_add_f32_e32 v146, v146, v147
	v_mov_b32_e32 v195, v146
; __device__ __forceinline__ void gemm_tile(const Params& P, const GArgs& ga, const TileDesc& td, int wid_s) {
;     ...
;       static_for<8>([&](auto ic2) __attribute__((always_inline)) {
;         constexpr int idx = b0 + decltype(ic2)::v; constexpr int ai = idx >> 4, m = (idx >> 2) & 3, j = idx & 3;
;         constexpr int rl = ai * HALF + m * 16 + j; constexpr int q = decltype(ic2)::v;
;         float4 v;
;         v.x = r[q].x + scale * acc[ai][0][m][0][j]; v.y = r[q].y + scale * acc[ai][0][m][1][j];
;         v.z = r[q].z + scale * acc[ai][1][m][0][j]; v.w = r[q].w + scale * acc[ai][1][m][1][j];
;         uint2 o; o.x = pack2(v.x, v.y); o.y = pack2(v.z, v.w);
;         *reinterpret_cast<uint2*>(hb + (size_t)rl * DM) = o;
;         float s = red16(v.x * v.x + v.y * v.y + v.z * v.z + v.w * v.w);
;         if (efr == 0) unsafeAtomicAdd(sso + rl, s);
;       });
.LBB0_651:
	s_or_b64 exec, exec, s[6:7]
	v_mov_b32_e32 v146, v34
	v_mov_b32_e32 v147, v38
	s_waitcnt vmcnt(7)
	v_pk_fma_f32 v[142:143], s[20:21], v[146:147], v[142:143]
	v_mov_b32_e32 v146, v46
	v_mov_b32_e32 v147, v42
	v_pk_fma_f32 v[144:145], s[20:21], v[146:147], v[144:145]
	v_cvt_pk_bf16_f32 v146, v142, v143
	v_pk_mul_f32 v[142:143], v[142:143], v[142:143]
	v_cvt_pk_bf16_f32 v147, v144, v145
	v_pk_mul_f32 v[144:145], v[144:145], v[144:145]
	v_add_f32_e32 v142, v143, v142
	v_add_f32_e32 v142, v144, v142
	v_add_f32_e32 v142, v145, v142
	s_mov_b32 s6, 0x90000
	v_add_co_u32_e32 v148, vcc, s6, v162
	v_add_f32_dpp v142, v142, v142 quad_perm:[1,0,3,2] row_mask:0xf bank_mask:0xf bound_ctrl:1
	s_nop 0
	v_addc_co_u32_e32 v149, vcc, 0, v163, vcc
	v_add_f32_dpp v142, v142, v142 quad_perm:[2,3,0,1] row_mask:0xf bank_mask:0xf bound_ctrl:1
	global_store_dwordx2 v[148:149], v[146:147], off nt
	s_nop 0
	v_add_f32_dpp v142, v142, v142 row_ror:4 row_mask:0xf bank_mask:0xf bound_ctrl:1
	s_nop 1
	v_mov_b32_dpp v143, v142 row_ror:8 row_mask:0xf bank_mask:0xf bound_ctrl:1
	s_and_saveexec_b64 s[6:7], s[0:1]
	s_cbranch_execz .LBB0_653
	v_add_f32_e32 v142, v142, v143
	v_mov_b32_e32 v196, v142
.LBB0_653:
	s_or_b64 exec, exec, s[6:7]
	v_mov_b32_e32 v142, v35
	v_mov_b32_e32 v143, v39
	s_waitcnt vmcnt(7)
	v_pk_fma_f32 v[138:139], s[20:21], v[142:143], v[138:139]
	v_mov_b32_e32 v142, v47
	v_mov_b32_e32 v143, v43
	v_pk_fma_f32 v[140:141], s[20:21], v[142:143], v[140:141]
	v_cvt_pk_bf16_f32 v142, v138, v139
	v_pk_mul_f32 v[138:139], v[138:139], v[138:139]
	v_cvt_pk_bf16_f32 v143, v140, v141
	v_pk_mul_f32 v[140:141], v[140:141], v[140:141]
	v_add_f32_e32 v138, v139, v138
	v_add_f32_e32 v138, v140, v138
	v_add_f32_e32 v138, v141, v138
	s_mov_b32 s6, 0x91000
	v_add_co_u32_e32 v144, vcc, s6, v162
	v_add_f32_dpp v138, v138, v138 quad_perm:[1,0,3,2] row_mask:0xf bank_mask:0xf bound_ctrl:1
	s_nop 0
	v_addc_co_u32_e32 v145, vcc, 0, v163, vcc
	v_add_f32_dpp v138, v138, v138 quad_perm:[2,3,0,1] row_mask:0xf bank_mask:0xf bound_ctrl:1
	global_store_dwordx2 v[144:145], v[142:143], off nt
	s_nop 0
	v_add_f32_dpp v138, v138, v138 row_ror:4 row_mask:0xf bank_mask:0xf bound_ctrl:1
	s_nop 1
	v_mov_b32_dpp v139, v138 row_ror:8 row_mask:0xf bank_mask:0xf bound_ctrl:1
	s_and_saveexec_b64 s[6:7], s[0:1]
	s_cbranch_execz .LBB0_655
	v_add_f32_e32 v138, v138, v139
	v_mov_b32_e32 v197, v138
.LBB0_655:
	s_or_b64 exec, exec, s[6:7]
	v_mov_b32_e32 v138, v36
	v_mov_b32_e32 v139, v40
	s_waitcnt vmcnt(7)
	v_pk_fma_f32 v[134:135], s[20:21], v[138:139], v[134:135]
	v_mov_b32_e32 v138, v48
	v_mov_b32_e32 v139, v44
	v_pk_fma_f32 v[136:137], s[20:21], v[138:139], v[136:137]
	v_cvt_pk_bf16_f32 v138, v134, v135
	v_pk_mul_f32 v[134:135], v[134:135], v[134:135]
	v_cvt_pk_bf16_f32 v139, v136, v137
	v_pk_mul_f32 v[136:137], v[136:137], v[136:137]
	v_add_f32_e32 v134, v135, v134
	v_add_f32_e32 v134, v136, v134
	v_add_f32_e32 v134, v137, v134
	s_mov_b32 s6, 0x92000
	v_add_co_u32_e32 v140, vcc, s6, v162
	v_add_f32_dpp v134, v134, v134 quad_perm:[1,0,3,2] row_mask:0xf bank_mask:0xf bound_ctrl:1
	s_nop 0
	v_addc_co_u32_e32 v141, vcc, 0, v163, vcc
	v_add_f32_dpp v134, v134, v134 quad_perm:[2,3,0,1] row_mask:0xf bank_mask:0xf bound_ctrl:1
	global_store_dwordx2 v[140:141], v[138:139], off nt
	s_nop 0
	v_add_f32_dpp v134, v134, v134 row_ror:4 row_mask:0xf bank_mask:0xf bound_ctrl:1
	s_nop 1
	v_mov_b32_dpp v135, v134 row_ror:8 row_mask:0xf bank_mask:0xf bound_ctrl:1
	s_and_saveexec_b64 s[6:7], s[0:1]
	s_cbranch_execz .LBB0_657
	v_add_f32_e32 v134, v134, v135
	v_mov_b32_e32 v198, v134
.LBB0_657:
	s_or_b64 exec, exec, s[6:7]
	v_mov_b32_e32 v134, v37
	v_mov_b32_e32 v135, v41
	s_waitcnt vmcnt(7)
	v_pk_fma_f32 v[130:131], s[20:21], v[134:135], v[130:131]
	v_mov_b32_e32 v134, v49
	v_mov_b32_e32 v135, v45
	v_pk_fma_f32 v[132:133], s[20:21], v[134:135], v[132:133]
	v_cvt_pk_bf16_f32 v134, v130, v131
	v_pk_mul_f32 v[130:131], v[130:131], v[130:131]
	v_cvt_pk_bf16_f32 v135, v132, v133
	v_pk_mul_f32 v[132:133], v[132:133], v[132:133]
	v_add_f32_e32 v130, v131, v130
	v_add_f32_e32 v130, v132, v130
	v_add_f32_e32 v130, v133, v130
	s_mov_b32 s6, 0x93000
	v_add_co_u32_e32 v136, vcc, s6, v162
	v_add_f32_dpp v130, v130, v130 quad_perm:[1,0,3,2] row_mask:0xf bank_mask:0xf bound_ctrl:1
	s_nop 0
	v_addc_co_u32_e32 v137, vcc, 0, v163, vcc
	v_add_f32_dpp v130, v130, v130 quad_perm:[2,3,0,1] row_mask:0xf bank_mask:0xf bound_ctrl:1
	global_store_dwordx2 v[136:137], v[134:135], off nt
	s_nop 0
	v_add_f32_dpp v130, v130, v130 row_ror:4 row_mask:0xf bank_mask:0xf bound_ctrl:1
	s_nop 1
	v_mov_b32_dpp v131, v130 row_ror:8 row_mask:0xf bank_mask:0xf bound_ctrl:1
	s_and_saveexec_b64 s[6:7], s[0:1]
	s_cbranch_execz .LBB0_659
	v_add_f32_e32 v130, v130, v131
	v_mov_b32_e32 v199, v130

; __device__ __forceinline__ void gemm_tile(const Params& P, const GArgs& ga, const TileDesc& td, int wid_s) {
;     ...
;       static_for<8>([&](auto ic2) __attribute__((always_inline)) {
;         constexpr int idx = b0 + decltype(ic2)::v; constexpr int ai = idx >> 4, m = (idx >> 2) & 3, j = idx & 3;
;         constexpr int rl = ai * HALF + m * 16 + j; constexpr int q = decltype(ic2)::v;
;         float4 v;
;         v.x = r[q].x + scale * acc[ai][0][m][0][j]; v.y = r[q].y + scale * acc[ai][0][m][1][j];
;         v.z = r[q].z + scale * acc[ai][1][m][0][j]; v.w = r[q].w + scale * acc[ai][1][m][1][j];
;         uint2 o; o.x = pack2(v.x, v.y); o.y = pack2(v.z, v.w);
;         *reinterpret_cast<uint2*>(hb + (size_t)rl * DM) = o;
;         float s = red16(v.x * v.x + v.y * v.y + v.z * v.z + v.w * v.w);
;         if (efr == 0) unsafeAtomicAdd(sso + rl, s);
;       });
.LBB0_663:
	v_mov_b32_e32 v170, v18
	v_mov_b32_e32 v171, v22
	s_waitcnt vmcnt(7)
	v_pk_fma_f32 v[158:159], s[20:21], v[170:171], v[158:159]
	v_mov_b32_e32 v170, v30
	v_mov_b32_e32 v171, v26
	v_pk_fma_f32 v[160:161], s[20:21], v[170:171], v[160:161]
	v_cvt_pk_bf16_f32 v170, v158, v159
	v_pk_mul_f32 v[158:159], v[158:159], v[158:159]
	v_cvt_pk_bf16_f32 v171, v160, v161
	v_pk_mul_f32 v[160:161], v[160:161], v[160:161]
	v_add_f32_e32 v158, v159, v158
	v_add_f32_e32 v158, v160, v158
	v_add_f32_e32 v158, v161, v158
	s_mov_b32 s4, 0xa0000
	v_add_co_u32_e32 v172, vcc, s4, v162
	v_add_f32_dpp v158, v158, v158 quad_perm:[1,0,3,2] row_mask:0xf bank_mask:0xf bound_ctrl:1
	s_nop 0
	v_addc_co_u32_e32 v173, vcc, 0, v163, vcc
	v_add_f32_dpp v158, v158, v158 quad_perm:[2,3,0,1] row_mask:0xf bank_mask:0xf bound_ctrl:1
	global_store_dwordx2 v[172:173], v[170:171], off nt
	s_nop 0
	v_add_f32_dpp v158, v158, v158 row_ror:4 row_mask:0xf bank_mask:0xf bound_ctrl:1
	s_nop 1
	v_mov_b32_dpp v159, v158 row_ror:8 row_mask:0xf bank_mask:0xf bound_ctrl:1
	s_and_saveexec_b64 s[4:5], s[0:1]
	s_cbranch_execz .LBB0_665
	v_add_f32_e32 v158, v158, v159
	v_mov_b32_e32 v204, v158
.LBB0_665:
	s_or_b64 exec, exec, s[4:5]
	v_mov_b32_e32 v158, v19
	v_mov_b32_e32 v159, v23
	s_waitcnt vmcnt(7)
	v_pk_fma_f32 v[154:155], s[20:21], v[158:159], v[154:155]
	v_mov_b32_e32 v158, v31
	v_mov_b32_e32 v159, v27
	v_pk_fma_f32 v[156:157], s[20:21], v[158:159], v[156:157]
	v_cvt_pk_bf16_f32 v158, v154, v155
	v_pk_mul_f32 v[154:155], v[154:155], v[154:155]
	v_cvt_pk_bf16_f32 v159, v156, v157
	v_pk_mul_f32 v[156:157], v[156:157], v[156:157]
	v_add_f32_e32 v154, v155, v154
	v_add_f32_e32 v154, v156, v154
	v_add_f32_e32 v154, v157, v154
	s_mov_b32 s4, 0xa1000
	v_add_co_u32_e32 v160, vcc, s4, v162
	v_add_f32_dpp v154, v154, v154 quad_perm:[1,0,3,2] row_mask:0xf bank_mask:0xf bound_ctrl:1
	s_nop 0
	v_addc_co_u32_e32 v161, vcc, 0, v163, vcc
	v_add_f32_dpp v154, v154, v154 quad_perm:[2,3,0,1] row_mask:0xf bank_mask:0xf bound_ctrl:1
	global_store_dwordx2 v[160:161], v[158:159], off nt
	s_nop 0
	v_add_f32_dpp v154, v154, v154 row_ror:4 row_mask:0xf bank_mask:0xf bound_ctrl:1
	s_nop 1
	v_mov_b32_dpp v155, v154 row_ror:8 row_mask:0xf bank_mask:0xf bound_ctrl:1
	s_and_saveexec_b64 s[4:5], s[0:1]
	s_cbranch_execz .LBB0_667
	v_add_f32_e32 v154, v154, v155
	v_mov_b32_e32 v205, v154
.LBB0_667:
	s_or_b64 exec, exec, s[4:5]
	v_mov_b32_e32 v154, v20
	v_mov_b32_e32 v155, v24
	s_waitcnt vmcnt(7)
	v_pk_fma_f32 v[150:151], s[20:21], v[154:155], v[150:151]
	v_mov_b32_e32 v154, v32
	v_mov_b32_e32 v155, v28
	v_pk_fma_f32 v[152:153], s[20:21], v[154:155], v[152:153]
	v_cvt_pk_bf16_f32 v154, v150, v151
	v_pk_mul_f32 v[150:151], v[150:151], v[150:151]
	v_cvt_pk_bf16_f32 v155, v152, v153
	v_pk_mul_f32 v[152:153], v[152:153], v[152:153]
	v_add_f32_e32 v150, v151, v150
	v_add_f32_e32 v150, v152, v150
	v_add_f32_e32 v150, v153, v150
	s_mov_b32 s4, 0xa2000
	v_add_co_u32_e32 v156, vcc, s4, v162
	v_add_f32_dpp v150, v150, v150 quad_perm:[1,0,3,2] row_mask:0xf bank_mask:0xf bound_ctrl:1
	s_nop 0
	v_addc_co_u32_e32 v157, vcc, 0, v163, vcc
	v_add_f32_dpp v150, v150, v150 quad_perm:[2,3,0,1] row_mask:0xf bank_mask:0xf bound_ctrl:1
	global_store_dwordx2 v[156:157], v[154:155], off nt
	s_nop 0
	v_add_f32_dpp v150, v150, v150 row_ror:4 row_mask:0xf bank_mask:0xf bound_ctrl:1
	s_nop 1
	v_mov_b32_dpp v151, v150 row_ror:8 row_mask:0xf bank_mask:0xf bound_ctrl:1
	s_and_saveexec_b64 s[4:5], s[0:1]
	s_cbranch_execz .LBB0_669
	v_add_f32_e32 v150, v150, v151
	v_mov_b32_e32 v206, v150
.LBB0_669:
	s_or_b64 exec, exec, s[4:5]
	v_mov_b32_e32 v150, v21
	v_mov_b32_e32 v151, v25
	s_waitcnt vmcnt(7)
	v_pk_fma_f32 v[146:147], s[20:21], v[150:151], v[146:147]
	v_mov_b32_e32 v150, v33
	v_mov_b32_e32 v151, v29
	v_pk_fma_f32 v[148:149], s[20:21], v[150:151], v[148:149]
	v_cvt_pk_bf16_f32 v150, v146, v147
	v_pk_mul_f32 v[146:147], v[146:147], v[146:147]
	v_cvt_pk_bf16_f32 v151, v148, v149
	v_pk_mul_f32 v[148:149], v[148:149], v[148:149]
	v_add_f32_e32 v146, v147, v146
	v_add_f32_e32 v146, v148, v146
	v_add_f32_e32 v146, v149, v146
	s_mov_b32 s4, 0xa3000
	v_add_co_u32_e32 v152, vcc, s4, v162
	v_add_f32_dpp v146, v146, v146 quad_perm:[1,0,3,2] row_mask:0xf bank_mask:0xf bound_ctrl:1
	s_nop 0
	v_addc_co_u32_e32 v153, vcc, 0, v163, vcc
	v_add_f32_dpp v146, v146, v146 quad_perm:[2,3,0,1] row_mask:0xf bank_mask:0xf bound_ctrl:1
	global_store_dwordx2 v[152:153], v[150:151], off nt
	s_nop 0
	v_add_f32_dpp v146, v146, v146 row_ror:4 row_mask:0xf bank_mask:0xf bound_ctrl:1
	s_nop 1
	v_mov_b32_dpp v147, v146 row_ror:8 row_mask:0xf bank_mask:0xf bound_ctrl:1
	s_and_saveexec_b64 s[4:5], s[0:1]
	s_cbranch_execz .LBB0_671
	v_add_f32_e32 v146, v146, v147
	v_mov_b32_e32 v207, v146
.LBB0_671:
	s_or_b64 exec, exec, s[4:5]
	v_mov_b32_e32 v146, v2
	v_mov_b32_e32 v147, v6
	s_waitcnt vmcnt(7)
	v_pk_fma_f32 v[142:143], s[20:21], v[146:147], v[142:143]
	v_mov_b32_e32 v146, v14
	v_mov_b32_e32 v147, v10
	v_pk_fma_f32 v[144:145], s[20:21], v[146:147], v[144:145]
	v_cvt_pk_bf16_f32 v146, v142, v143
	v_pk_mul_f32 v[142:143], v[142:143], v[142:143]
	v_cvt_pk_bf16_f32 v147, v144, v145
	v_pk_mul_f32 v[144:145], v[144:145], v[144:145]
	v_add_f32_e32 v142, v143, v142
	v_add_f32_e32 v142, v144, v142
	v_add_f32_e32 v142, v145, v142
	s_mov_b32 s4, 0xb0000
	v_add_co_u32_e32 v148, vcc, s4, v162
	v_add_f32_dpp v142, v142, v142 quad_perm:[1,0,3,2] row_mask:0xf bank_mask:0xf bound_ctrl:1
	s_nop 0
	v_addc_co_u32_e32 v149, vcc, 0, v163, vcc
	v_add_f32_dpp v142, v142, v142 quad_perm:[2,3,0,1] row_mask:0xf bank_mask:0xf bound_ctrl:1
	global_store_dwordx2 v[148:149], v[146:147], off nt
	s_nop 0
	v_add_f32_dpp v142, v142, v142 row_ror:4 row_mask:0xf bank_mask:0xf bound_ctrl:1
	s_nop 1
	v_mov_b32_dpp v143, v142 row_ror:8 row_mask:0xf bank_mask:0xf bound_ctrl:1
	s_and_saveexec_b64 s[4:5], s[0:1]
	s_cbranch_execz .LBB0_673
	v_add_f32_e32 v142, v142, v143
	v_mov_b32_e32 v208, v142
; __device__ __forceinline__ void gemm_tile(const Params& P, const GArgs& ga, const TileDesc& td, int wid_s) {
;     ...
;       static_for<8>([&](auto ic2) __attribute__((always_inline)) {
;         constexpr int idx = b0 + decltype(ic2)::v; constexpr int ai = idx >> 4, m = (idx >> 2) & 3, j = idx & 3;
;         constexpr int rl = ai * HALF + m * 16 + j; constexpr int q = decltype(ic2)::v;
;         float4 v;
;         v.x = r[q].x + scale * acc[ai][0][m][0][j]; v.y = r[q].y + scale * acc[ai][0][m][1][j];
;         v.z = r[q].z + scale * acc[ai][1][m][0][j]; v.w = r[q].w + scale * acc[ai][1][m][1][j];
;         uint2 o; o.x = pack2(v.x, v.y); o.y = pack2(v.z, v.w);
;         *reinterpret_cast<uint2*>(hb + (size_t)rl * DM) = o;
;         float s = red16(v.x * v.x + v.y * v.y + v.z * v.z + v.w * v.w);
;         if (efr == 0) unsafeAtomicAdd(sso + rl, s);
;       });
.LBB0_673:
	s_or_b64 exec, exec, s[4:5]
	v_mov_b32_e32 v142, v3
	v_mov_b32_e32 v143, v7
	s_waitcnt vmcnt(7)
	v_pk_fma_f32 v[138:139], s[20:21], v[142:143], v[138:139]
	v_mov_b32_e32 v142, v15
	v_mov_b32_e32 v143, v11
	v_pk_fma_f32 v[140:141], s[20:21], v[142:143], v[140:141]
	v_cvt_pk_bf16_f32 v142, v138, v139
	v_pk_mul_f32 v[138:139], v[138:139], v[138:139]
	v_cvt_pk_bf16_f32 v143, v140, v141
	v_pk_mul_f32 v[140:141], v[140:141], v[140:141]
	v_add_f32_e32 v138, v139, v138
	v_add_f32_e32 v138, v140, v138
	v_add_f32_e32 v138, v141, v138
	s_mov_b32 s4, 0xb1000
	v_add_co_u32_e32 v144, vcc, s4, v162
	v_add_f32_dpp v138, v138, v138 quad_perm:[1,0,3,2] row_mask:0xf bank_mask:0xf bound_ctrl:1
	s_nop 0
	v_addc_co_u32_e32 v145, vcc, 0, v163, vcc
	v_add_f32_dpp v138, v138, v138 quad_perm:[2,3,0,1] row_mask:0xf bank_mask:0xf bound_ctrl:1
	global_store_dwordx2 v[144:145], v[142:143], off nt
	s_nop 0
	v_add_f32_dpp v138, v138, v138 row_ror:4 row_mask:0xf bank_mask:0xf bound_ctrl:1
	s_nop 1
	v_mov_b32_dpp v139, v138 row_ror:8 row_mask:0xf bank_mask:0xf bound_ctrl:1
	s_and_saveexec_b64 s[4:5], s[0:1]
	s_cbranch_execz .LBB0_675
	v_add_f32_e32 v138, v138, v139
	v_mov_b32_e32 v209, v138
.LBB0_675:
	s_or_b64 exec, exec, s[4:5]
	v_mov_b32_e32 v138, v4
	v_mov_b32_e32 v139, v8
	s_waitcnt vmcnt(7)
	v_pk_fma_f32 v[134:135], s[20:21], v[138:139], v[134:135]
	v_mov_b32_e32 v138, v16
	v_mov_b32_e32 v139, v12
	v_pk_fma_f32 v[136:137], s[20:21], v[138:139], v[136:137]
	v_cvt_pk_bf16_f32 v138, v134, v135
	v_pk_mul_f32 v[134:135], v[134:135], v[134:135]
	v_cvt_pk_bf16_f32 v139, v136, v137
	v_pk_mul_f32 v[136:137], v[136:137], v[136:137]
	v_add_f32_e32 v134, v135, v134
	v_add_f32_e32 v134, v136, v134
	v_add_f32_e32 v134, v137, v134
	s_mov_b32 s4, 0xb2000
	v_add_co_u32_e32 v140, vcc, s4, v162
	v_add_f32_dpp v134, v134, v134 quad_perm:[1,0,3,2] row_mask:0xf bank_mask:0xf bound_ctrl:1
	s_nop 0
	v_addc_co_u32_e32 v141, vcc, 0, v163, vcc
	v_add_f32_dpp v134, v134, v134 quad_perm:[2,3,0,1] row_mask:0xf bank_mask:0xf bound_ctrl:1
	global_store_dwordx2 v[140:141], v[138:139], off nt
	s_nop 0
	v_add_f32_dpp v134, v134, v134 row_ror:4 row_mask:0xf bank_mask:0xf bound_ctrl:1
	s_nop 1
	v_mov_b32_dpp v135, v134 row_ror:8 row_mask:0xf bank_mask:0xf bound_ctrl:1
	s_and_saveexec_b64 s[4:5], s[0:1]
	s_cbranch_execz .LBB0_677
	v_add_f32_e32 v134, v134, v135
	v_mov_b32_e32 v210, v134
.LBB0_677:
	s_or_b64 exec, exec, s[4:5]
	v_mov_b32_e32 v134, v5
	v_mov_b32_e32 v135, v9
	s_waitcnt vmcnt(7)
	v_pk_fma_f32 v[130:131], s[20:21], v[134:135], v[130:131]
	v_mov_b32_e32 v134, v17
	v_mov_b32_e32 v135, v13
	v_pk_fma_f32 v[132:133], s[20:21], v[134:135], v[132:133]
	v_cvt_pk_bf16_f32 v134, v130, v131
	v_pk_mul_f32 v[130:131], v[130:131], v[130:131]
	v_cvt_pk_bf16_f32 v135, v132, v133
	v_pk_mul_f32 v[132:133], v[132:133], v[132:133]
	v_add_f32_e32 v130, v131, v130
	v_add_f32_e32 v130, v132, v130
	v_add_f32_e32 v130, v133, v130
	s_mov_b32 s4, 0xb3000
	v_add_co_u32_e32 v136, vcc, s4, v162
	v_add_f32_dpp v130, v130, v130 quad_perm:[1,0,3,2] row_mask:0xf bank_mask:0xf bound_ctrl:1
	s_nop 0
	v_addc_co_u32_e32 v137, vcc, 0, v163, vcc
	v_add_f32_dpp v130, v130, v130 quad_perm:[2,3,0,1] row_mask:0xf bank_mask:0xf bound_ctrl:1
	global_store_dwordx2 v[136:137], v[134:135], off nt
	s_nop 0
	v_add_f32_dpp v130, v130, v130 row_ror:4 row_mask:0xf bank_mask:0xf bound_ctrl:1
	s_nop 1
	v_mov_b32_dpp v131, v130 row_ror:8 row_mask:0xf bank_mask:0xf bound_ctrl:1
	s_and_saveexec_b64 s[4:5], s[0:1]
	s_cbranch_execz .LBB0_679
	v_add_f32_e32 v130, v130, v131
	v_mov_b32_e32 v211, v130
.LBB0_679:
	s_or_b64 exec, exec, s[4:5]
	s_and_saveexec_b64 s[4:5], s[0:1]
	global_atomic_add_f32 v[164:165], v176, off
	global_atomic_add_f32 v[164:165], v177, off offset:4
	global_atomic_add_f32 v[164:165], v178, off offset:8
	global_atomic_add_f32 v[164:165], v179, off offset:12
	global_atomic_add_f32 v[164:165], v180, off offset:64
	global_atomic_add_f32 v[164:165], v181, off offset:68
	global_atomic_add_f32 v[164:165], v182, off offset:72
	global_atomic_add_f32 v[164:165], v183, off offset:76
	global_atomic_add_f32 v[164:165], v184, off offset:128
	global_atomic_add_f32 v[164:165], v185, off offset:132
	global_atomic_add_f32 v[164:165], v186, off offset:136
	global_atomic_add_f32 v[164:165], v187, off offset:140
	global_atomic_add_f32 v[164:165], v188, off offset:192
	global_atomic_add_f32 v[164:165], v189, off offset:196
	global_atomic_add_f32 v[164:165], v190, off offset:200
	global_atomic_add_f32 v[164:165], v191, off offset:204
	global_atomic_add_f32 v[164:165], v192, off offset:512
	global_atomic_add_f32 v[164:165], v193, off offset:516
	global_atomic_add_f32 v[164:165], v194, off offset:520
	global_atomic_add_f32 v[164:165], v195, off offset:524
	global_atomic_add_f32 v[164:165], v196, off offset:576
	global_atomic_add_f32 v[164:165], v197, off offset:580
	global_atomic_add_f32 v[164:165], v198, off offset:584
	global_atomic_add_f32 v[164:165], v199, off offset:588
	global_atomic_add_f32 v[164:165], v204, off offset:640
	global_atomic_add_f32 v[164:165], v205, off offset:644
	global_atomic_add_f32 v[164:165], v206, off offset:648
	global_atomic_add_f32 v[164:165], v207, off offset:652
	global_atomic_add_f32 v[164:165], v208, off offset:704
	global_atomic_add_f32 v[164:165], v209, off offset:708
	global_atomic_add_f32 v[164:165], v210, off offset:712
	global_atomic_add_f32 v[164:165], v211, off offset:716
	s_or_b64 exec, exec, s[4:5]
	s_mov_b64 s[0:1], 0
